# v61 + R2Y: retention-output unit takes its decay logits from a per-phase lane table via v_readlane (no VMEM wait at the unit head)
# baseline (speedup 1.0000x reference)
; #define LAS __attribute__((address_space(3)))
; __device__ __forceinline__ unsigned f2bf(float f) { unsigned u = __builtin_bit_cast(unsigned, f); return (u + 0x7fffu + ((u >> 16) & 1u)) >> 16; }
; __device__ __forceinline__ int crow16(int r, int hi) { return (r & 3) + 8 * (r >> 2) + 4 * hi; }
; #define IDS() int tid_ = threadIdx.x; asm volatile("" : "+v"(tid_)); const int lane_ = tid_ & 63, wave_ = __builtin_amdgcn_readfirstlane(tid_ >> 6); const int gw_ = vcu * NWAVES + wave_; (void)lane_; (void)gw_
; __device__ __forceinline__ void ret_out_unit(int unit, const bf16* RQ, const bf16* RK, const bf16* RV, const bf16* RG, const float* decay_l, const float* RETC, bf16* MIX, lds_t* lds, int tid, int lane, int wave) {
;     ...
;     for (int tt = 0; tt < 2; ++tt) { const int tile = wave * 2 + tt, it = tile >> 2, jt = tile & 3; f32x16 acc = {};
;         mma32<4>(acc, Qs + 32 * it * RT_LDD, RT_LDD, Ks + 32 * jt * RT_LDD, RT_LDD, lane);
;         const int j = 32 * jt + (lane & 31);
; #pragma unroll
;         for (int r = 0; r < 16; ++r) { const int i = 32 * it + crow16(r, lane >> 5); const float dd = (float)(i - j); const float w = acc[r] * __expf(dd >= 0.f ? lgf * dd : -lgb * dd);
;             *(LAS unsigned short*)(Ws + i * RT_LDK + j * 2) = (unsigned short)f2bf(w); } }
;     __syncthreads();
;     f32x16 o;
;     { const int it = wave >> 1, vt = wave & 1; f32x16 a1 = {}, a2 = {}, a3 = {};
;         mma32<8>(a1, Ws + 32 * it * RT_LDK, RT_LDK, Vt + 32 * vt * RT_LDK, RT_LDK, lane);
;         mma32<4>(a2, Qs + 32 * it * RT_LDD, RT_LDD, Sft + 32 * vt * RT_LDD, RT_LDD, lane);
;         mma32<4>(a3, Qs + 32 * it * RT_LDD, RT_LDD, Sbt + 32 * vt * RT_LDD, RT_LDD, lane);
; #pragma unroll
;         for (int r = 0; r < 16; ++r) { const int i = 32 * it + crow16(r, lane >> 5); o[r] = a1[r] + __expf(lgf * (float)(i + 1)) * a2[r] + __expf(lgb * (float)(128 - i)) * a3[r]; } }
; __global__ void __launch_bounds__(NTHR, 2) trunk_fwd(Args a) {
;     ...
;             { IDS(); for (int u = (vcu + G - 64) % G; u < 32 * 34; u += G) { if (!need_ctx && (u % 34) >= 32) continue; ret_out_unit(u, RQ, RK, RV, RG, a.ret_decay + l * 8, RETC, MIX, lds, tid_, lane_, wave_); } }
.LBB0_775:
	s_waitcnt vmcnt(0) lgkmcnt(0)
	v_readlane_b32 s2, v255, 11
	v_mov_b32_e32 v2, v212
	v_readlane_b32 s3, v255, 12
	s_mov_b32 s62, s60
	s_barrier
	s_and_b64 vcc, exec, s[2:3]
	v_readfirstlane_b32 s0, v2
	s_cbranch_vccz .LBB0_784
	v_and_b32_e32 v8, 31, v2
	v_lshrrev_b32_e32 v11, 1, v2
	s_ashr_i32 s0, s0, 6
	v_mul_u32_u24_e32 v9, 0x90, v8
	v_and_b32_e32 v11, 16, v11
	s_lshl_b32 s1, s0, 1
	s_lshl_b32 s6, s0, 4
	v_add3_u32 v65, 0, v9, v11
	v_lshrrev_b32_e32 v9, 3, v2
	s_and_b32 s1, s1, 2
	s_and_b32 s7, s6, 0xffffffe0
	v_and_b32_e32 v9, 4, v9
	v_lshlrev_b32_e32 v4, 3, v2
	v_readlane_b32 s2, v255, 51
	v_or_b32_e32 v12, s7, v9
	v_lshl_or_b32 v13, s1, 5, v8
	v_ashrrev_i32_e32 v5, 31, v4
	v_readlane_b32 s3, v255, 52
	v_sub_u32_e32 v14, v12, v13
	v_cvt_f32_i32_e32 v67, v14
	v_lshl_add_u64 v[58:59], v[4:5], 2, s[2:3]
	v_cmp_gt_i32_e64 s[2:3], 0, v14
	v_or_b32_e32 v14, 1, v12
	v_sub_u32_e32 v15, v14, v13
	v_writelane_b32 v253, s2, 47
	v_cvt_f32_i32_e32 v69, v15
	v_ashrrev_i32_e32 v62, 2, v2
	v_writelane_b32 v253, s3, 48
	v_cmp_gt_i32_e64 s[2:3], 0, v15
	v_or_b32_e32 v15, 2, v12
	v_lshlrev_b32_e32 v0, 4, v2
	v_bfe_u32 v2, v2, 3, 3
	v_writelane_b32 v253, s2, 49
	v_sub_u32_e32 v16, v15, v13
	v_cvt_f32_i32_e32 v70, v16
	v_writelane_b32 v253, s3, 50
	v_cmp_gt_i32_e64 s[2:3], 0, v16
	v_or_b32_e32 v16, s7, v2
	v_or_b32_e32 v17, 3, v16
	v_writelane_b32 v253, s2, 51
	v_sub_u32_e32 v18, v17, v13
	v_cvt_f32_i32_e32 v71, v18
	v_writelane_b32 v253, s3, 52
	v_cmp_gt_i32_e64 s[2:3], 0, v18
	v_or_b32_e32 v18, 8, v12
	v_sub_u32_e32 v19, v18, v13
	v_writelane_b32 v253, s2, 53
	v_cvt_f32_i32_e32 v73, v19
	v_or_b32_e32 v16, 11, v16
	v_writelane_b32 v253, s3, 54
	v_cmp_gt_i32_e64 s[2:3], 0, v19
	v_or_b32_e32 v19, 9, v12
	v_sub_u32_e32 v20, v19, v13
	v_cvt_f32_i32_e32 v74, v20
	v_cmp_gt_i32_e64 s[16:17], 0, v20
	v_or_b32_e32 v20, 10, v12
	v_sub_u32_e32 v21, v20, v13
	v_cvt_f32_i32_e32 v75, v21
	v_cmp_gt_i32_e64 s[18:19], 0, v21
	v_sub_u32_e32 v21, v16, v13
	v_or_b32_e32 v9, s6, v9
	v_cvt_f32_i32_e32 v76, v21
	v_cmp_gt_i32_e64 s[20:21], 0, v21
	v_or_b32_e32 v21, 16, v9
	v_sub_u32_e32 v22, v21, v13
	v_cvt_f32_i32_e32 v78, v22
	v_cmp_gt_i32_e64 s[22:23], 0, v22
	v_or_b32_e32 v22, 17, v9
	v_sub_u32_e32 v23, v22, v13
	v_cvt_f32_i32_e32 v80, v23
	v_cmp_gt_i32_e64 s[24:25], 0, v23
	v_or_b32_e32 v23, 18, v9
	v_sub_u32_e32 v24, v23, v13
	v_or_b32_e32 v2, s6, v2
	v_cvt_f32_i32_e32 v82, v24
	v_cmp_gt_i32_e64 s[26:27], 0, v24
	v_or_b32_e32 v24, 19, v2
	v_sub_u32_e32 v25, v24, v13
	v_cvt_f32_i32_e32 v84, v25
	v_cmp_gt_i32_e64 s[28:29], 0, v25
	v_or_b32_e32 v25, 24, v9
	v_sub_u32_e32 v26, v25, v13
	s_mul_i32 s8, s7, 0x90
	v_cvt_f32_i32_e32 v86, v26
	v_cmp_gt_i32_e64 s[30:31], 0, v26
	v_or_b32_e32 v26, 25, v9
	s_add_i32 s8, s8, 0
	v_sub_u32_e32 v27, v26, v13
	v_mov_b32_e32 v10, s8
	v_readlane_b32 s8, v255, 50
	v_cvt_f32_i32_e32 v88, v27
	v_cmp_gt_i32_e64 s[34:35], 0, v27
	v_or_b32_e32 v27, 26, v9
	v_or_b32_e32 v2, 27, v2
	s_mul_i32 s63, s1, 0x1200
	v_lshl_add_u32 v66, v13, 1, s8
	v_sub_u32_e32 v28, v27, v13
	v_sub_u32_e32 v13, v2, v13
	s_or_b32 s1, s1, 1
	v_cvt_f32_i32_e32 v92, v13
	v_cmp_gt_i32_e64 s[38:39], 0, v13
	v_lshl_or_b32 v13, s1, 5, v8
	v_cvt_f32_i32_e32 v90, v28
	v_cmp_gt_i32_e64 s[36:37], 0, v28
	v_sub_u32_e32 v28, v12, v13
	v_cvt_f32_i32_e32 v95, v28
	v_cmp_gt_i32_e64 s[40:41], 0, v28
	v_sub_u32_e32 v28, v14, v13
	v_cvt_f32_i32_e32 v111, v14
	v_sub_u32_e32 v14, 0x80, v14
	v_cvt_f32_i32_e32 v130, v14
	v_or_b32_e32 v14, 3, v12
	v_cvt_f32_i32_e32 v131, v14
	v_sub_u32_e32 v14, 0x80, v15
	v_cvt_f32_i32_e32 v132, v14
	v_add_u32_e32 v14, 1, v17
	v_cvt_f32_i32_e32 v133, v14
	v_sub_u32_e32 v14, 0x80, v17
	v_cvt_f32_i32_e32 v96, v28
	v_cmp_gt_i32_e64 s[42:43], 0, v28
	v_sub_u32_e32 v28, v15, v13
	v_cvt_f32_i32_e32 v134, v14
	v_sub_u32_e32 v14, 0x80, v18
	v_cvt_f32_i32_e32 v97, v28
	v_cmp_gt_i32_e64 s[44:45], 0, v28
	v_sub_u32_e32 v28, v17, v13
	v_cvt_f32_i32_e32 v136, v14
	v_sub_u32_e32 v14, 0x80, v19
	v_cvt_f32_i32_e32 v98, v28
	v_cmp_gt_i32_e64 s[46:47], 0, v28
	v_sub_u32_e32 v28, v18, v13
	v_cvt_f32_i32_e32 v138, v14
	v_or_b32_e32 v14, 11, v12
	v_cvt_f32_i32_e32 v99, v28
	v_cmp_gt_i32_e64 s[48:49], 0, v28
	v_sub_u32_e32 v28, v19, v13
	v_cvt_f32_i32_e32 v139, v14
	v_sub_u32_e32 v14, 0x80, v20
	v_cvt_f32_i32_e32 v100, v28
	v_cmp_gt_i32_e64 s[50:51], 0, v28
	v_sub_u32_e32 v28, v20, v13
	v_cvt_f32_i32_e32 v140, v14
	v_add_u32_e32 v14, 1, v16
	v_cvt_f32_i32_e32 v101, v28
	v_cmp_gt_i32_e64 s[52:53], 0, v28
	v_sub_u32_e32 v28, v16, v13
	v_cvt_f32_i32_e32 v141, v14
	v_sub_u32_e32 v14, 0x80, v16
	v_cvt_f32_i32_e32 v102, v28
	v_cmp_gt_i32_e64 s[54:55], 0, v28
	v_sub_u32_e32 v28, v21, v13
	v_cvt_f32_i32_e32 v142, v14
	v_sub_u32_e32 v14, 0x80, v21
	s_waitcnt vmcnt(2)
; #define LAS __attribute__((address_space(3)))
; __device__ __forceinline__ unsigned f2bf(float f) { unsigned u = __builtin_bit_cast(unsigned, f); return (u + 0x7fffu + ((u >> 16) & 1u)) >> 16; }
; __device__ __forceinline__ float log_sigmoid(float x) { return fminf(x, 0.f) - log1pf(expf(-fabsf(x))); }
; __device__ __forceinline__ void ret_out_unit(int unit, const bf16* RQ, const bf16* RK, const bf16* RV, const bf16* RG, const float* decay_l, const float* RETC, bf16* MIX, lds_t* lds, int tid, int lane, int wave) {
;     const int c = unit % 34, bh = unit / 34, h = bh & 3, b = bh >> 2; const int m0 = chunk_row0(b, c);
;     lds_t* Qs = lds; lds_t* Ks = Qs + 128 * RT_LDD; lds_t* Vt = Ks + 128 * RT_LDD; lds_t* Sft = Vt + 64 * RT_LDK; lds_t* Sbt = Sft + 64 * RT_LDD; lds_t* Ws = Sbt + 64 * RT_LDD;
;     const float lgf = log_sigmoid(decay_l[h]), lgb = log_sigmoid(decay_l[4 + h]);
;     v4u gpre[2]; { const v4u* gp0 = (const v4u*)(RG + (size_t)(m0 + (tid >> 2)) * 256 + h * 64 + (tid & 3) * 16); gpre[0] = gp0[0]; gpre[1] = gp0[1]; }
;     { const float* base = RETC + ((size_t)bh * 34 + c) * 2 * 4096 + tid * 8;
;         const f32x4 sf0 = *(const f32x4*)base, sf1 = *(const f32x4*)(base + 4), sb0 = *(const f32x4*)(base + 4096), sb1 = *(const f32x4*)(base + 4096 + 4);
;         const int d = tid >> 3, v0 = (tid & 7) * 8;
; #pragma unroll
;         for (int e = 0; e < 4; ++e) { *(LAS unsigned short*)(Sft + (v0 + e) * RT_LDD + d * 2) = (unsigned short)f2bf(sf0[e]); *(LAS unsigned short*)(Sft + (v0 + 4 + e) * RT_LDD + d * 2) = (unsigned short)f2bf(sf1[e]);
;             *(LAS unsigned short*)(Sbt + (v0 + e) * RT_LDD + d * 2) = (unsigned short)f2bf(sb0[e]); *(LAS unsigned short*)(Sbt + (v0 + 4 + e) * RT_LDD + d * 2) = (unsigned short)f2bf(sb1[e]); } }
;     { const int j = tid >> 2, d0 = (tid & 3) * 16; const size_t go = (size_t)(m0 + j) * 256 + h * 64 + d0;
;         const v4u* qp = (const v4u*)(RQ + go); const v4u* kp = (const v4u*)(RK + go); const v4u* vp = (const v4u*)(RV + go);
; #pragma unroll
;         for (int q = 0; q < 2; ++q) { *(LAS v4u*)(Qs + j * RT_LDD + (d0 + 8 * q) * 2) = qp[q]; *(LAS v4u*)(Ks + j * RT_LDD + (d0 + 8 * q) * 2) = kp[q]; const v4u vw = vp[q];
	v_cvt_f32_i32_e32 v103, v28
	v_cmp_gt_i32_e64 s[56:57], 0, v28
	v_sub_u32_e32 v28, v22, v13
	v_cvt_f32_i32_e32 v144, v14
	v_add_u32_e32 v14, 1, v22
	v_cvt_f32_i32_e32 v104, v28
	v_cmp_gt_i32_e64 s[58:59], 0, v28
	v_sub_u32_e32 v28, v23, v13
	v_cvt_f32_i32_e32 v145, v14
	v_sub_u32_e32 v14, 0x80, v22
	v_cvt_f32_i32_e32 v105, v28
	v_cmp_gt_i32_e64 s[60:61], 0, v28
	v_sub_u32_e32 v28, v24, v13
	v_cvt_f32_i32_e32 v146, v14
	v_or_b32_e32 v14, 19, v9
	v_writelane_b32 v253, s2, 55
	v_cvt_f32_i32_e32 v106, v28
	v_cmp_gt_i32_e64 s[14:15], 0, v28
	v_sub_u32_e32 v28, v25, v13
	s_lshl_b32 s0, s0, 5
	v_cvt_f32_i32_e32 v147, v14
	v_sub_u32_e32 v14, 0x80, v23
	v_writelane_b32 v253, s3, 56
	v_cvt_f32_i32_e32 v107, v28
	v_cmp_gt_i32_e64 s[2:3], 0, v28
	v_sub_u32_e32 v28, v26, v13
	s_mulk_i32 s7, 0x110
	s_and_b32 s0, s0, 32
	v_cvt_f32_i32_e32 v148, v14
	v_add_u32_e32 v14, 1, v24
	s_mul_i32 s79, s1, 0x1200
	v_lshl_add_u32 v94, v13, 1, s8
	v_cvt_f32_i32_e32 v108, v28
	v_cmp_gt_i32_e64 s[4:5], 0, v28
	v_sub_u32_e32 v28, v27, v13
	v_sub_u32_e32 v13, v2, v13
	s_add_i32 s1, s8, s7
	s_mul_i32 s6, s0, 0x110
	v_cvt_f32_i32_e32 v149, v14
	v_sub_u32_e32 v14, 0x80, v24
	v_or_b32_e32 v9, 27, v9
	v_cvt_f32_i32_e32 v110, v13
	v_cmp_gt_i32_e64 s[70:71], 0, v13
	s_add_i32 s6, s6, 0
	v_mov_b32_e32 v13, s1
	s_lshl_b32 s1, s0, 7
	v_cvt_f32_i32_e32 v150, v14
	v_sub_u32_e32 v14, 0x80, v25
	v_cvt_f32_i32_e32 v155, v9
	v_sub_u32_e32 v9, 0x80, v27
	s_sub_i32 s1, s6, s1
	v_cvt_f32_i32_e32 v152, v14
	v_add_u32_e32 v14, 1, v26
	v_cvt_f32_i32_e32 v156, v9
	v_add_u32_e32 v9, 1, v2
	s_lshl_b32 s0, s0, 2
	s_movk_i32 s10, 0x90
	s_movk_i32 s9, 0x110
	v_cvt_f32_i32_e32 v109, v28
	v_cmp_gt_i32_e64 s[68:69], 0, v28
	v_mov_b32_e32 v28, s6
	v_mov_b32_e32 v29, s1
	v_sub_u32_e32 v30, 0x80, v12
	v_cvt_f32_i32_e32 v153, v14
	v_sub_u32_e32 v14, 0x80, v26
	v_cvt_f32_i32_e32 v157, v9
	v_sub_u32_e32 v9, 0x80, v2
	s_add_i32 s0, s8, s0
	v_and_b32_e32 v0, 48, v0
	v_mad_u32_u24 v10, v8, s10, v10
	v_mad_u32_u24 v13, v8, s9, v13
	v_mad_u32_u24 v28, v8, s9, v28
	v_mad_u32_u24 v29, v8, s10, v29
	v_cvt_f32_i32_e32 v112, v30
	v_cvt_f32_i32_e32 v113, v15
	v_cvt_f32_i32_e32 v135, v19
	v_cvt_f32_i32_e32 v137, v20
	v_cvt_f32_i32_e32 v143, v22
	v_cvt_f32_i32_e32 v151, v26
	v_cvt_f32_i32_e32 v154, v14
	v_cvt_f32_i32_e32 v158, v9
	v_lshl_add_u32 v8, v8, 2, s0
	s_movk_i32 s0, 0x104
	v_and_b32_e32 v3, 56, v4
	v_and_b32_e32 v4, -2, v62
	v_mul_lo_u32 v5, v62, s10
	v_lshlrev_b32_e32 v64, 1, v0
	v_mul_lo_u32 v68, v12, s9
	v_mul_lo_u32 v72, v17, s9
	v_mul_lo_u32 v77, v16, s9
	v_mul_lo_u32 v81, v22, s9
	v_mul_lo_u32 v83, v23, s9
	v_mul_lo_u32 v9, v12, s0
	v_mul_lo_u32 v12, v17, s0
	v_mul_lo_u32 v14, v16, s0
	v_mul_lo_u32 v16, v22, s0
	v_mul_lo_u32 v17, v23, s0
	v_mul_lo_u32 v22, v62, s0
	v_lshlrev_b32_e32 v23, 2, v0
	v_add_u32_e32 v4, 0, v4
	v_mul_u32_u24_e32 v3, 0x90, v3
	v_add_u32_e32 v63, 0, v5
	v_lshlrev_b32_e32 v5, 1, v62
	v_mad_u32_u24 v6, v0, s9, 0
	v_or_b32_e32 v7, 16, v64
	v_mul_lo_u32 v79, v21, s9
	v_mul_lo_u32 v93, v2, s9
	v_mul_lo_u32 v15, v21, s0
	v_mul_lo_u32 v18, v24, s0
	v_mul_lo_u32 v19, v25, s0
	v_mul_lo_u32 v20, v26, s0
	v_mul_lo_u32 v21, v27, s0
	v_mul_lo_u32 v2, v2, s0
	v_add3_u32 v159, s8, v22, v23
	v_readlane_b32 s8, v255, 10
	v_mul_lo_u32 v85, v24, s9
	v_mul_lo_u32 v87, v25, s9
	v_mul_lo_u32 v89, v26, s9
	v_mul_lo_u32 v91, v27, s9
	s_lshl_b32 s6, s8, 7
	s_lshl_b32 s7, s62, 7
	v_lshlrev_b32_e32 v0, 1, v0
	v_add_u32_e32 v160, v4, v3
	v_add_u32_e32 v161, v6, v5
	v_add_u32_e32 v162, v63, v7
	v_add_u32_e32 v163, v10, v11
	v_add_u32_e32 v164, v13, v11
	v_add_u32_e32 v165, v28, v11
	v_add_u32_e32 v166, v29, v11
	v_add_u32_e32 v167, v8, v9
	v_add_u32_e32 v168, v8, v12
	v_add_u32_e32 v169, v8, v14
	v_add_u32_e32 v170, v8, v15
	v_add_u32_e32 v171, v8, v16
	v_add_u32_e32 v172, v8, v17
	v_add_u32_e32 v173, v8, v18
	v_add_u32_e32 v174, v8, v19
	v_add_u32_e32 v175, v8, v20
	v_add_u32_e32 v176, v8, v21
	v_add_u32_e32 v177, v8, v2
	v_mbcnt_lo_u32_b32 v245, -1, 0
	v_mbcnt_hi_u32_b32 v245, -1, v245
	v_and_b32_e32 v245, 7, v245
	v_lshlrev_b32_e32 v245, 2, v245
	global_load_dword v244, v245, s[82:83]
	s_waitcnt vmcnt(0)
	s_branch .LBB0_779
.LBB0_777:
	s_and_b32 s0, s10, 3
	s_lshl_b32 s13, s0, 2
	s_add_u32 s99, s0, 4
	v_readlane_b32 s98, v244, s0
	v_readlane_b32 s99, v244, s99
	s_nop 0
	v_mov_b32_e32 v25, s98
	v_mov_b32_e32 v24, s99
	s_lshl_b32 s84, s0, 7
	s_mul_hi_i32 s1, s10, 34
	s_ashr_i32 s10, s11, 31
	s_add_u32 s0, s12, s11
	s_addc_u32 s1, s1, s10
	s_lshl_b64 s[0:1], s[0:1], 15
	v_lshl_add_u64 v[14:15], v[58:59], 0, s[0:1]
	s_mov_b32 s0, 0xbfb8aa3b
	s_mov_b32 s1, 0xb2a5705f
	s_mov_b32 s10, 0x42ce8ed0
	s_mov_b32 s11, 0x33800000
	s_mov_b64 s[12:13], 0x4000
	v_add_u32_e32 v60, s9, v62
	v_ashrrev_i32_e32 v61, 31, v60
	global_load_dwordx4 v[180:183], v[14:15], off offset:16
	global_load_dwordx4 v[184:187], v[14:15], off
	v_lshl_add_u64 v[192:193], v[14:15], 0, s[12:13]
	global_load_dwordx4 v[188:191], v[192:193], off
	global_load_dwordx4 v[192:195], v[192:193], off offset:16
	v_lshlrev_b64 v[242:243], 9, v[60:61]
	v_readlane_b32 s98, v255, 3
	v_readlane_b32 s99, v255, 4
	v_or3_b32 v242, s84, v0, v242
	v_readlane_b32 s100, v252, 30
	v_readlane_b32 s101, v252, 31
	v_lshl_add_u64 v[206:207], s[98:99], 0, v[242:243]
	v_readlane_b32 s98, v252, 32
	v_readlane_b32 s99, v252, 33
	v_lshl_add_u64 v[230:231], s[100:101], 0, v[242:243]
	global_load_dwordx4 v[202:205], v[206:207], off offset:16
	global_load_dwordx4 v[206:209], v[206:207], off
	v_lshl_add_u64 v[238:239], s[98:99], 0, v[242:243]
	global_load_dwordx4 v[226:229], v[230:231], off offset:16
	global_load_dwordx4 v[230:233], v[230:231], off
	global_load_dwordx4 v[234:237], v[238:239], off
; __device__ __forceinline__ float log_sigmoid(float x) { return fminf(x, 0.f) - log1pf(expf(-fabsf(x))); }
; __device__ __forceinline__ void ret_out_unit(int unit, const bf16* RQ, const bf16* RK, const bf16* RV, const bf16* RG, const float* decay_l, const float* RETC, bf16* MIX, lds_t* lds, int tid, int lane, int wave) {
;     ...
;     const float lgf = log_sigmoid(decay_l[h]), lgb = log_sigmoid(decay_l[4 + h]);
;     v4u gpre[2]; { const v4u* gp0 = (const v4u*)(RG + (size_t)(m0 + (tid >> 2)) * 256 + h * 64 + (tid & 3) * 16); gpre[0] = gp0[0]; gpre[1] = gp0[1]; }
	global_load_dwordx4 v[238:241], v[238:239], off offset:16
	v_mul_f32_e64 v2, |v25|, s0
	v_fma_f32 v3, |v25|, s0, -v2
	v_rndne_f32_e32 v4, v2
	v_fma_f32 v3, |v25|, s1, v3
	v_sub_f32_e32 v2, v2, v4
	v_add_f32_e32 v2, v2, v3
	v_cvt_i32_f32_e32 v4, v4
	v_exp_f32_e32 v2, v2
	v_mul_f32_e64 v3, |v24|, s0
	v_rndne_f32_e32 v5, v3
	v_cmp_ngt_f32_e64 vcc, |v25|, s10
	v_ldexp_f32 v2, v2, v4
	v_fma_f32 v4, |v24|, s0, -v3
	v_fma_f32 v4, |v24|, s1, v4
	v_sub_f32_e32 v3, v3, v5
	v_add_f32_e32 v3, v3, v4
	v_cvt_i32_f32_e32 v5, v5
	v_exp_f32_e32 v3, v3
	v_cndmask_b32_e32 v2, 0, v2, vcc
	v_cmp_ngt_f32_e64 vcc, |v24|, s10
	s_mov_b32 s0, 0xc2b17218
	v_ldexp_f32 v3, v3, v5
	v_cndmask_b32_e32 v3, 0, v3, vcc
	v_cmp_nlt_f32_e64 vcc, |v25|, s0
	s_mov_b32 s1, 0x3f317218
	s_mov_b32 s10, 0x7f800000
	v_cndmask_b32_e32 v4, v219, v2, vcc
	v_cmp_nlt_f32_e64 vcc, |v24|, s0
	v_add_f32_e32 v5, 1.0, v4
	v_frexp_mant_f32_e32 v6, v5
	v_cndmask_b32_e32 v26, v219, v3, vcc
	v_cvt_f64_f32_e32 v[2:3], v5
	s_mov_b32 s0, 0x3f2aaaab
	v_frexp_exp_i32_f64_e32 v2, v[2:3]
	v_cmp_gt_f32_e32 vcc, s0, v6
	v_add_f32_e32 v7, 1.0, v26
	v_frexp_mant_f32_e32 v8, v7
	v_subbrev_co_u32_e32 v6, vcc, 0, v2, vcc
	v_cvt_f64_f32_e32 v[2:3], v7
	v_frexp_exp_i32_f64_e32 v2, v[2:3]
	v_cmp_gt_f32_e32 vcc, s0, v8
	s_movk_i32 s0, 0x4000
	s_nop 0
	v_subbrev_co_u32_e32 v18, vcc, 0, v2, vcc
	v_add_f32_e32 v2, -1.0, v5
	v_sub_f32_e32 v3, v2, v5
	v_sub_f32_e32 v2, v4, v2
	v_add_f32_e32 v3, 1.0, v3
	v_add_f32_e32 v2, v2, v3
	v_sub_u32_e32 v3, 0, v6
	v_cvt_f32_i32_e32 v6, v6
	v_ldexp_f32 v5, v5, v3
	v_ldexp_f32 v2, v2, v3
	v_add_f32_e32 v3, -1.0, v5
	v_add_f32_e32 v8, 1.0, v5
	v_add_f32_e32 v9, 1.0, v3
	v_add_f32_e32 v10, -1.0, v8
	v_sub_f32_e32 v9, v5, v9
	v_sub_f32_e32 v5, v5, v10
	v_mul_f32_e32 v10, 0x3f317218, v6
	v_add_f32_e32 v9, v2, v9
	v_add_f32_e32 v2, v2, v5
	v_fma_f32 v5, v6, s1, -v10
	v_add_f32_e32 v12, v8, v2
	v_fmac_f32_e32 v5, 0xb102e308, v6
	v_sub_f32_e32 v6, v8, v12
	v_rcp_f32_e32 v8, v12
	v_add_f32_e32 v13, v10, v5
	v_add_f32_e32 v11, v3, v9
	v_add_f32_e32 v2, v2, v6
	v_sub_f32_e32 v6, v13, v10
	v_sub_f32_e32 v3, v3, v11
	v_sub_f32_e32 v5, v5, v6
	v_mul_f32_e32 v6, v11, v8
	v_add_f32_e32 v3, v9, v3
	v_mul_f32_e32 v9, v12, v6
	v_fma_f32 v10, v6, v12, -v9
	v_fmac_f32_e32 v10, v6, v2
	v_add_f32_e32 v16, v9, v10
	v_sub_f32_e32 v17, v11, v16
	v_sub_f32_e32 v9, v16, v9
	v_sub_f32_e32 v11, v11, v17
	v_sub_f32_e32 v9, v9, v10
	v_sub_f32_e32 v10, v11, v16
	v_add_f32_e32 v3, v3, v10
	v_add_f32_e32 v3, v9, v3
	v_add_f32_e32 v9, v17, v3
	v_mul_f32_e32 v10, v8, v9
	v_sub_f32_e32 v11, v17, v9
	v_mul_f32_e32 v16, v12, v10
	v_add_f32_e32 v3, v3, v11
	v_add_f32_e32 v11, v6, v10
	v_fma_f32 v12, v10, v12, -v16
	v_sub_f32_e32 v6, v11, v6
	v_fmac_f32_e32 v12, v10, v2
	v_sub_f32_e32 v2, v10, v6
	v_add_f32_e32 v6, v16, v12
	v_sub_f32_e32 v10, v6, v16
	v_sub_f32_e32 v16, v9, v6
	v_sub_f32_e32 v9, v9, v16
	v_sub_f32_e32 v6, v9, v6
	v_sub_f32_e32 v10, v10, v12
	v_add_f32_e32 v3, v3, v6
	v_add_f32_e32 v3, v10, v3
	v_add_f32_e32 v3, v16, v3
	v_mul_f32_e32 v3, v8, v3
	v_add_f32_e32 v2, v2, v3
	v_add_f32_e32 v3, v11, v2
	v_mul_f32_e32 v6, v3, v3
	v_fmamk_f32 v10, v6, 0x3e9b6dac, v217
	v_sub_f32_e32 v8, v3, v11
	v_ldexp_f32 v9, v3, 1
	v_mul_f32_e32 v3, v3, v6
	v_fmaak_f32 v6, v6, v10, 0x3f2aaada
	v_mul_f32_e32 v3, v3, v6
	v_add_f32_e32 v6, v9, v3
	v_sub_f32_e32 v2, v2, v8
	v_sub_f32_e32 v8, v6, v9
	v_ldexp_f32 v2, v2, 1
	v_sub_f32_e32 v3, v3, v8
	v_add_f32_e32 v2, v2, v3
	v_add_f32_e32 v3, v6, v2
	v_sub_f32_e32 v6, v3, v6
	v_add_f32_e32 v8, v13, v3
	v_sub_f32_e32 v2, v2, v6
	v_sub_f32_e32 v6, v8, v13
	v_sub_f32_e32 v9, v8, v6
	v_sub_f32_e32 v3, v3, v6
	v_add_f32_e32 v6, v5, v2
	v_sub_f32_e32 v9, v13, v9
	v_sub_f32_e32 v10, v6, v5
	v_add_f32_e32 v3, v3, v9
	v_sub_f32_e32 v9, v6, v10
	v_sub_f32_e32 v2, v2, v10
	v_sub_f32_e32 v5, v5, v9
	v_add_f32_e32 v3, v6, v3
	v_add_f32_e32 v2, v2, v5
	v_add_f32_e32 v5, v8, v3
	v_sub_f32_e32 v6, v5, v8
	v_sub_f32_e32 v3, v3, v6
	v_add_f32_e32 v2, v2, v3
	v_add_f32_e32 v2, v5, v2
	v_cmp_neq_f32_e32 vcc, s10, v4
	s_nop 1
	v_cndmask_b32_e32 v2, v219, v2, vcc
	v_cmp_lt_f32_e64 vcc, |v4|, s11
	s_nop 1
	v_cndmask_b32_e32 v27, v2, v4, vcc
	v_add_f32_e32 v2, -1.0, v7
	v_sub_f32_e32 v3, v2, v7
	v_add_f32_e32 v3, 1.0, v3
	v_sub_f32_e32 v2, v26, v2
	v_add_f32_e32 v2, v2, v3
	v_sub_u32_e32 v3, 0, v18
	v_ldexp_f32 v4, v7, v3
	v_ldexp_f32 v2, v2, v3
	v_add_f32_e32 v3, -1.0, v4
	v_add_f32_e32 v7, 1.0, v4
	v_add_f32_e32 v5, 1.0, v3
	v_add_f32_e32 v8, -1.0, v7
	v_sub_f32_e32 v5, v4, v5
	v_sub_f32_e32 v4, v4, v8
	v_add_f32_e32 v5, v2, v5
	v_add_f32_e32 v2, v2, v4
	v_add_f32_e32 v19, v7, v2
	v_rcp_f32_e32 v20, v19
	v_add_f32_e32 v6, v3, v5
	v_sub_f32_e32 v3, v3, v6
	v_add_f32_e32 v12, v5, v3
	v_sub_f32_e32 v3, v7, v19
	v_mul_f32_e32 v22, v6, v20
	v_add_f32_e32 v21, v2, v3
	v_mul_f32_e32 v2, v19, v22
	v_fma_f32 v13, v22, v19, -v2
	v_fmac_f32_e32 v13, v22, v21
	v_add_f32_e32 v16, v2, v13
	v_sub_f32_e32 v23, v6, v16
	v_sub_f32_e32 v17, v16, v2
	v_sub_f32_e32 v28, v6, v23
	v_sub_f32_e32 v16, v28, v16
	v_add_f32_e32 v12, v12, v16
	v_sub_f32_e32 v13, v17, v13
	v_add_f32_e32 v28, v13, v12
	v_add_f32_e32 v29, v23, v28
	v_mul_f32_e32 v30, v20, v29
	v_mul_f32_e32 v31, v19, v30
	v_fma_f32 v19, v30, v19, -v31
	v_fmac_f32_e32 v19, v30, v21
	v_sub_f32_e32 v21, v23, v29
	v_add_f32_e32 v23, v31, v19
	v_add_f32_e32 v21, v28, v21
	v_sub_f32_e32 v28, v23, v31
	v_sub_f32_e32 v31, v29, v23
	v_sub_f32_e32 v29, v29, v31
	v_sub_f32_e32 v23, v29, v23
	v_add_f32_e32 v21, v21, v23
	v_sub_f32_e32 v19, v28, v19
	v_add_f32_e32 v19, v19, v21
	v_add_f32_e32 v19, v31, v19
	v_cvt_f32_i32_e32 v18, v18
	v_mul_f32_e32 v19, v20, v19
	v_add_f32_e32 v20, v22, v30
	v_sub_f32_e32 v21, v20, v22
	v_sub_f32_e32 v21, v30, v21
	v_add_f32_e32 v19, v21, v19
	v_mul_f32_e32 v51, 0x3f317218, v18
	v_add_f32_e32 v48, v20, v19
	v_fma_f32 v52, v18, s1, -v51
	v_fmac_f32_e32 v52, 0xb102e308, v18
	v_sub_f32_e32 v18, v48, v20
	v_readlane_b32 s0, v252, 34
	v_sub_f32_e32 v53, v19, v18
	v_lshlrev_b64 v[18:19], 9, v[60:61]
	v_readlane_b32 s1, v252, 35
	v_mul_f32_e32 v49, v48, v48
	v_fmamk_f32 v21, v49, 0x3e9b6dac, v217
	v_lshl_add_u64 v[22:23], s[0:1], 0, v[18:19]
	v_fmaak_f32 v50, v49, v21, 0x3f2aaada
	v_add_f32_e32 v54, v51, v52
	v_lshl_add_u64 v[22:23], v[22:23], 0, s[84:85]
	v_lshl_add_u64 v[22:23], v[22:23], 0, v[0:1]
	v_cmp_neq_f32_e32 vcc, s10, v26
	s_nop 0
	s_nop 0
	s_nop 0
	v_sub_f32_e32 v20, v54, v51
	v_mul_f32_e32 v21, v48, v49
	v_sub_f32_e32 v178, v52, v20
	v_ldexp_f32 v20, v48, 1
	v_mul_f32_e32 v48, v21, v50
	v_add_f32_e32 v49, v20, v48
	v_sub_f32_e32 v50, v49, v20
	v_ldexp_f32 v51, v53, 1
	v_sub_f32_e32 v48, v48, v50
	v_add_f32_e32 v48, v51, v48
	v_add_f32_e32 v50, v49, v48
	v_sub_f32_e32 v49, v50, v49
	v_sub_f32_e32 v48, v48, v49
	v_add_f32_e32 v49, v54, v50
	v_sub_f32_e32 v51, v49, v54
	v_sub_f32_e32 v52, v49, v51
	v_sub_f32_e32 v52, v54, v52
	v_sub_f32_e32 v50, v50, v51
	v_add_f32_e32 v179, v50, v52
	global_load_dwordx4 v[50:53], v[22:23], off offset:16
	global_load_dwordx4 v[54:57], v[22:23], off
	s_waitcnt vmcnt(10)
; #define LAS __attribute__((address_space(3)))
; __device__ __forceinline__ void ret_out_unit(int unit, const bf16* RQ, const bf16* RK, const bf16* RV, const bf16* RG, const float* decay_l, const float* RETC, bf16* MIX, lds_t* lds, int tid, int lane, int wave) {
;     ...
;     { const float* base = RETC + ((size_t)bh * 34 + c) * 2 * 4096 + tid * 8;
;         const f32x4 sf0 = *(const f32x4*)base, sf1 = *(const f32x4*)(base + 4), sb0 = *(const f32x4*)(base + 4096), sb1 = *(const f32x4*)(base + 4096 + 4);
;         const int d = tid >> 3, v0 = (tid & 7) * 8;
; #pragma unroll
;         for (int e = 0; e < 4; ++e) { *(LAS unsigned short*)(Sft + (v0 + e) * RT_LDD + d * 2) = (unsigned short)f2bf(sf0[e]); *(LAS unsigned short*)(Sft + (v0 + 4 + e) * RT_LDD + d * 2) = (unsigned short)f2bf(sf1[e]);
;             *(LAS unsigned short*)(Sbt + (v0 + e) * RT_LDD + d * 2) = (unsigned short)f2bf(sb0[e]); *(LAS unsigned short*)(Sbt + (v0 + 4 + e) * RT_LDD + d * 2) = (unsigned short)f2bf(sb1[e]); } }
;     { const int j = tid >> 2, d0 = (tid & 3) * 16; const size_t go = (size_t)(m0 + j) * 256 + h * 64 + d0;
;         const v4u* qp = (const v4u*)(RQ + go); const v4u* kp = (const v4u*)(RK + go); const v4u* vp = (const v4u*)(RV + go);
; #pragma unroll
;         for (int q = 0; q < 2; ++q) { *(LAS v4u*)(Qs + j * RT_LDD + (d0 + 8 * q) * 2) = qp[q]; *(LAS v4u*)(Ks + j * RT_LDD + (d0 + 8 * q) * 2) = kp[q]; const v4u vw = vp[q];
; #pragma unroll
;             for (int e = 0; e < 4; ++e) { const unsigned vv = vw[e]; const int d = d0 + q * 8 + 2 * e;
;                 *(LAS unsigned short*)(Vt + d * RT_LDK + j * 2) = (unsigned short)(vv & 0xffffu); *(LAS unsigned short*)(Vt + (d + 1) * RT_LDK + j * 2) = (unsigned short)(vv >> 16); } } }
;     __syncthreads();
; #pragma unroll
;     for (int tt = 0; tt < 2; ++tt) { const int tile = wave * 2 + tt, it = tile >> 2, jt = tile & 3; f32x16 acc = {};
;         mma32<4>(acc, Qs + 32 * it * RT_LDD, RT_LDD, Ks + 32 * jt * RT_LDD, RT_LDD, lane);
;         const int j = 32 * jt + (lane & 31);
; #pragma unroll
;         for (int r = 0; r < 16; ++r) { const int i = 32 * it + crow16(r, lane >> 5); const float dd = (float)(i - j); const float w = acc[r] * __expf(dd >= 0.f ? lgf * dd : -lgb * dd);
;             *(LAS unsigned short*)(Ws + i * RT_LDK + j * 2) = (unsigned short)f2bf(w); } }
	v_bfe_u32 v22, v184, 16, 1
	v_add3_u32 v6, v184, v22, s33
	ds_write_b16_d16_hi v160, v6 offset:54272
	v_bfe_u32 v6, v180, 16, 1
	v_add3_u32 v2, v180, v6, s33
	ds_write_b16_d16_hi v160, v2 offset:54848
	s_waitcnt vmcnt(9)
	v_bfe_u32 v2, v188, 16, 1
	v_add3_u32 v2, v188, v2, s33
	ds_write_b16_d16_hi v160, v2 offset:63488
	s_waitcnt vmcnt(8)
	v_bfe_u32 v2, v192, 16, 1
	v_add3_u32 v2, v192, v2, s33
	ds_write_b16_d16_hi v160, v2 offset:64064
	v_bfe_u32 v2, v185, 16, 1
	v_add3_u32 v2, v185, v2, s33
	ds_write_b16_d16_hi v160, v2 offset:54416
	v_bfe_u32 v2, v181, 16, 1
	v_add3_u32 v2, v181, v2, s33
	ds_write_b16_d16_hi v160, v2 offset:54992
	v_bfe_u32 v2, v189, 16, 1
	v_add3_u32 v2, v189, v2, s33
	ds_write_b16_d16_hi v160, v2 offset:63632
	v_bfe_u32 v2, v193, 16, 1
	v_add3_u32 v2, v193, v2, s33
	ds_write_b16_d16_hi v160, v2 offset:64208
	v_bfe_u32 v2, v186, 16, 1
	v_add3_u32 v2, v186, v2, s33
	ds_write_b16_d16_hi v160, v2 offset:54560
	v_bfe_u32 v2, v182, 16, 1
	v_add3_u32 v2, v182, v2, s33
	ds_write_b16_d16_hi v160, v2 offset:55136
	v_bfe_u32 v2, v190, 16, 1
	v_add3_u32 v2, v190, v2, s33
	ds_write_b16_d16_hi v160, v2 offset:63776
	v_bfe_u32 v2, v194, 16, 1
	v_add3_u32 v2, v194, v2, s33
	ds_write_b16_d16_hi v160, v2 offset:64352
	v_bfe_u32 v2, v187, 16, 1
	v_add3_u32 v2, v187, v2, s33
	ds_write_b16_d16_hi v160, v2 offset:54704
	v_bfe_u32 v2, v183, 16, 1
	v_add3_u32 v2, v183, v2, s33
	ds_write_b16_d16_hi v160, v2 offset:55280
	v_bfe_u32 v2, v191, 16, 1
	v_add3_u32 v2, v191, v2, s33
	ds_write_b16_d16_hi v160, v2 offset:63920
	v_bfe_u32 v2, v195, 16, 1
	v_add3_u32 v2, v195, v2, s33
	ds_write_b16_d16_hi v160, v2 offset:64496
	v_add_u32_e32 v2, v63, v64
	s_waitcnt vmcnt(6)
	ds_write_b128 v2, v[206:209]
	s_waitcnt vmcnt(4)
	ds_write_b128 v2, v[230:233] offset:18432
	s_waitcnt vmcnt(3)
	ds_write_b16 v161, v234 offset:36864
	ds_write_b16_d16_hi v161, v234 offset:37136
	ds_write_b16 v161, v235 offset:37408
	ds_write_b16_d16_hi v161, v235 offset:37680
	ds_write_b16 v161, v236 offset:37952
	ds_write_b16_d16_hi v161, v236 offset:38224
	ds_write_b16 v161, v237 offset:38496
	ds_write_b16_d16_hi v161, v237 offset:38768
	ds_write_b128 v162, v[202:205]
	ds_write_b128 v162, v[226:229] offset:18432
	s_waitcnt vmcnt(2)
	ds_write_b16 v161, v238 offset:39040
	ds_write_b16_d16_hi v161, v238 offset:39312
	ds_write_b16 v161, v239 offset:39584
	ds_write_b16_d16_hi v161, v239 offset:39856
	ds_write_b16 v161, v240 offset:40128
	ds_write_b16_d16_hi v161, v240 offset:40400
	ds_write_b16 v161, v241 offset:40672
	ds_write_b16_d16_hi v161, v241 offset:40944
	s_waitcnt lgkmcnt(0)
	s_barrier
	ds_read_b128 v[2:5], v163
	v_add_u32_e32 v32, s63, v65
	ds_read_b128 v[6:9], v32 offset:18432
	v_add_f32_e32 v180, v178, v48
	v_sub_f32_e32 v181, v180, v178
	v_sub_f32_e32 v182, v180, v181
	v_sub_f32_e32 v10, v178, v182
	v_sub_f32_e32 v11, v48, v181
	v_add_f32_e32 v22, v11, v10
	s_waitcnt lgkmcnt(0)
	v_mfma_f32_32x32x16_bf16 v[2:17], v[2:5], v[6:9], 0
	ds_read_b128 v[18:21], v163 offset:32
	ds_read_b128 v[28:31], v32 offset:18464
	v_add_f32_e32 v23, v180, v179
	v_add_f32_e32 v33, v49, v23
	v_sub_f32_e32 v34, v33, v49
	v_sub_f32_e32 v23, v23, v34
	v_add_f32_e32 v22, v22, v23
	v_add_f32_e32 v22, v33, v22
	s_waitcnt lgkmcnt(0)
	v_mfma_f32_32x32x16_bf16 v[2:17], v[18:21], v[28:31], v[2:17]
	ds_read_b128 v[18:21], v163 offset:64
	ds_read_b128 v[28:31], v32 offset:18496
	v_cndmask_b32_e32 v22, v219, v22, vcc
	v_cmp_lt_f32_e64 vcc, |v26|, s11
	v_max_f32_e32 v37, v24, v24
	v_readlane_b32 s0, v253, 47
	v_cndmask_b32_e32 v26, v22, v26, vcc
	s_waitcnt lgkmcnt(0)
	v_mfma_f32_32x32x16_bf16 v[2:17], v[18:21], v[28:31], v[2:17]
	v_max_f32_e32 v22, v25, v25
	v_min_f32_e32 v36, 0, v22
	ds_read_b128 v[22:25], v163 offset:96
	ds_read_b128 v[32:35], v32 offset:18528
	v_min_f32_e32 v18, 0, v37
	v_sub_f32_e32 v179, v36, v27
	v_sub_f32_e32 v178, v18, v26
	v_readlane_b32 s1, v253, 48
	s_waitcnt lgkmcnt(0)
	v_mfma_f32_32x32x16_bf16 v[2:17], v[22:25], v[32:35], v[2:17]
	v_add_u32_e32 v30, s79, v65
	v_cndmask_b32_e64 v18, v179, -v178, s[0:1]
	v_mul_f32_e32 v18, v18, v67
	v_readlane_b32 s0, v253, 49
	v_mul_f32_e32 v18, 0x3fb8aa3b, v18
	v_readlane_b32 s1, v253, 50
	v_exp_f32_e32 v18, v18
	s_nop 0
	v_cndmask_b32_e64 v19, v179, -v178, s[0:1]
	v_mul_f32_e32 v19, v19, v69
	v_mul_f32_e32 v19, 0x3fb8aa3b, v19
	v_exp_f32_e32 v19, v19
	v_mul_f32_e32 v2, v2, v18
	v_bfe_u32 v18, v2, 16, 1
	v_readlane_b32 s0, v253, 51
	v_add3_u32 v2, v2, v18, s33
	v_add_u32_e32 v18, v66, v68
	v_readlane_b32 s1, v253, 52
	ds_write_b16_d16_hi v18, v2
	v_mul_f32_e32 v2, v3, v19
	v_cndmask_b32_e64 v3, v179, -v178, s[0:1]
	v_mul_f32_e32 v3, v3, v70
	v_mul_f32_e32 v3, 0x3fb8aa3b, v3
	v_exp_f32_e32 v3, v3
	v_bfe_u32 v19, v2, 16, 1
	v_readlane_b32 s0, v253, 53
	v_add3_u32 v2, v2, v19, s33
	v_readlane_b32 s1, v253, 54
	ds_write_b16_d16_hi v18, v2 offset:272
	v_mul_f32_e32 v2, v4, v3
	v_cndmask_b32_e64 v3, v179, -v178, s[0:1]
	v_mul_f32_e32 v3, v3, v71
	v_mul_f32_e32 v3, 0x3fb8aa3b, v3
	v_exp_f32_e32 v3, v3
	v_bfe_u32 v4, v2, 16, 1
	v_readlane_b32 s0, v253, 55
	v_add3_u32 v2, v2, v4, s33
	v_readlane_b32 s1, v253, 56
	ds_write_b16_d16_hi v18, v2 offset:544
	v_mul_f32_e32 v2, v5, v3
	v_cndmask_b32_e64 v4, v179, -v178, s[0:1]
	v_bfe_u32 v3, v2, 16, 1
	v_mul_f32_e32 v4, v4, v73
	v_mul_f32_e32 v4, 0x3fb8aa3b, v4
	v_add3_u32 v2, v2, v3, s33
	v_add_u32_e32 v3, v66, v72
	v_exp_f32_e32 v4, v4
	ds_write_b16_d16_hi v3, v2
	v_cndmask_b32_e64 v3, v179, -v178, s[16:17]
	v_mul_f32_e32 v3, v3, v74
	v_mul_f32_e32 v3, 0x3fb8aa3b, v3
	v_exp_f32_e32 v3, v3
	v_mul_f32_e32 v2, v6, v4
	v_bfe_u32 v4, v2, 16, 1
	v_add3_u32 v2, v2, v4, s33
	ds_write_b16_d16_hi v18, v2 offset:2176
; #define LAS __attribute__((address_space(3)))
; __device__ __forceinline__ unsigned f2bf(float f) { unsigned u = __builtin_bit_cast(unsigned, f); return (u + 0x7fffu + ((u >> 16) & 1u)) >> 16; }
; __device__ __forceinline__ int crow16(int r, int hi) { return (r & 3) + 8 * (r >> 2) + 4 * hi; }
; __device__ __forceinline__ void ret_out_unit(int unit, const bf16* RQ, const bf16* RK, const bf16* RV, const bf16* RG, const float* decay_l, const float* RETC, bf16* MIX, lds_t* lds, int tid, int lane, int wave) {
;     ...
;     for (int tt = 0; tt < 2; ++tt) { const int tile = wave * 2 + tt, it = tile >> 2, jt = tile & 3; f32x16 acc = {};
;         mma32<4>(acc, Qs + 32 * it * RT_LDD, RT_LDD, Ks + 32 * jt * RT_LDD, RT_LDD, lane);
;         const int j = 32 * jt + (lane & 31);
; #pragma unroll
;         for (int r = 0; r < 16; ++r) { const int i = 32 * it + crow16(r, lane >> 5); const float dd = (float)(i - j); const float w = acc[r] * __expf(dd >= 0.f ? lgf * dd : -lgb * dd);
;             *(LAS unsigned short*)(Ws + i * RT_LDK + j * 2) = (unsigned short)f2bf(w); } }
	v_mul_f32_e32 v2, v7, v3
	v_cndmask_b32_e64 v3, v179, -v178, s[18:19]
	v_mul_f32_e32 v3, v3, v75
	v_mul_f32_e32 v3, 0x3fb8aa3b, v3
	v_exp_f32_e32 v3, v3
	v_bfe_u32 v4, v2, 16, 1
	v_add3_u32 v2, v2, v4, s33
	ds_write_b16_d16_hi v18, v2 offset:2448
	v_mul_f32_e32 v2, v8, v3
	v_cndmask_b32_e64 v3, v179, -v178, s[20:21]
	v_mul_f32_e32 v3, v3, v76
	v_mul_f32_e32 v3, 0x3fb8aa3b, v3
	v_bfe_u32 v4, v2, 16, 1
	v_exp_f32_e32 v3, v3
	v_add3_u32 v2, v2, v4, s33
	v_cndmask_b32_e64 v4, v179, -v178, s[22:23]
	v_mul_f32_e32 v4, v4, v78
	v_mul_f32_e32 v4, 0x3fb8aa3b, v4
	v_exp_f32_e32 v4, v4
	ds_write_b16_d16_hi v18, v2 offset:2720
	v_mul_f32_e32 v2, v9, v3
	v_bfe_u32 v3, v2, 16, 1
	v_add3_u32 v2, v2, v3, s33
	v_add_u32_e32 v3, v66, v77
	ds_write_b16_d16_hi v3, v2
	v_mul_f32_e32 v2, v10, v4
	v_cndmask_b32_e64 v4, v179, -v178, s[24:25]
	v_mul_f32_e32 v4, v4, v80
	v_mul_f32_e32 v4, 0x3fb8aa3b, v4
	v_exp_f32_e32 v4, v4
	v_bfe_u32 v3, v2, 16, 1
	v_add3_u32 v2, v2, v3, s33
	v_add_u32_e32 v3, v66, v79
	ds_write_b16_d16_hi v3, v2
	v_mul_f32_e32 v2, v11, v4
	v_cndmask_b32_e64 v4, v179, -v178, s[26:27]
	v_mul_f32_e32 v4, v4, v82
	v_mul_f32_e32 v4, 0x3fb8aa3b, v4
	v_exp_f32_e32 v4, v4
	v_bfe_u32 v3, v2, 16, 1
	v_add3_u32 v2, v2, v3, s33
	v_add_u32_e32 v3, v66, v81
	ds_write_b16_d16_hi v3, v2
	v_mul_f32_e32 v2, v12, v4
	v_cndmask_b32_e64 v4, v179, -v178, s[28:29]
	v_mul_f32_e32 v4, v4, v84
	v_mul_f32_e32 v4, 0x3fb8aa3b, v4
	v_exp_f32_e32 v4, v4
	v_bfe_u32 v3, v2, 16, 1
	v_add3_u32 v2, v2, v3, s33
	v_add_u32_e32 v3, v66, v83
	ds_write_b16_d16_hi v3, v2
	v_mul_f32_e32 v2, v13, v4
	v_cndmask_b32_e64 v4, v179, -v178, s[30:31]
	v_mul_f32_e32 v4, v4, v86
	v_mul_f32_e32 v4, 0x3fb8aa3b, v4
	v_exp_f32_e32 v4, v4
	v_bfe_u32 v3, v2, 16, 1
	v_add3_u32 v2, v2, v3, s33
	v_add_u32_e32 v3, v66, v85
	ds_write_b16_d16_hi v3, v2
	v_mul_f32_e32 v2, v14, v4
	v_cndmask_b32_e64 v4, v179, -v178, s[34:35]
	v_mul_f32_e32 v4, v4, v88
	v_mul_f32_e32 v4, 0x3fb8aa3b, v4
	v_exp_f32_e32 v4, v4
	v_bfe_u32 v3, v2, 16, 1
	v_add3_u32 v2, v2, v3, s33
	v_add_u32_e32 v3, v66, v87
	ds_write_b16_d16_hi v3, v2
	v_mul_f32_e32 v2, v15, v4
	v_cndmask_b32_e64 v4, v179, -v178, s[36:37]
	v_mul_f32_e32 v4, v4, v90
	v_mul_f32_e32 v4, 0x3fb8aa3b, v4
	v_exp_f32_e32 v4, v4
	v_bfe_u32 v3, v2, 16, 1
	v_add3_u32 v2, v2, v3, s33
	v_add_u32_e32 v3, v66, v89
	ds_write_b16_d16_hi v3, v2
	v_mul_f32_e32 v2, v16, v4
	v_cndmask_b32_e64 v4, v179, -v178, s[38:39]
	v_mul_f32_e32 v4, v4, v92
	v_mul_f32_e32 v4, 0x3fb8aa3b, v4
	v_exp_f32_e32 v4, v4
	v_bfe_u32 v3, v2, 16, 1
	v_add3_u32 v2, v2, v3, s33
	v_add_u32_e32 v3, v66, v91
	ds_write_b16_d16_hi v3, v2
	v_mul_f32_e32 v2, v17, v4
	v_bfe_u32 v3, v2, 16, 1
	v_add3_u32 v2, v2, v3, s33
	v_add_u32_e32 v3, v66, v93
	ds_write_b16_d16_hi v3, v2
	ds_read_b128 v[2:5], v163
	ds_read_b128 v[6:9], v30 offset:18432
	ds_read_b128 v[18:21], v163 offset:32
	ds_read_b128 v[22:25], v30 offset:18464
	s_waitcnt lgkmcnt(2)
	v_mfma_f32_32x32x16_bf16 v[2:17], v[2:5], v[6:9], 0
	v_readlane_b32 s0, v255, 56
	v_readlane_b32 s1, v255, 57
	s_waitcnt lgkmcnt(0)
	v_mfma_f32_32x32x16_bf16 v[2:17], v[18:21], v[22:25], v[2:17]
	ds_read_b128 v[18:21], v163 offset:64
	ds_read_b128 v[22:25], v30 offset:18496
	ds_read_b128 v[26:29], v163 offset:96
	ds_read_b128 v[30:33], v30 offset:18528
	s_waitcnt lgkmcnt(2)
	v_mfma_f32_32x32x16_bf16 v[2:17], v[18:21], v[22:25], v[2:17]
	v_cndmask_b32_e64 v18, v179, -v178, s[40:41]
	v_mul_f32_e32 v18, v18, v95
	v_mul_f32_e32 v18, 0x3fb8aa3b, v18
	v_exp_f32_e32 v18, v18
	v_cndmask_b32_e64 v19, v179, -v178, s[42:43]
	v_mul_f32_e32 v19, v19, v96
	v_mul_f32_e32 v19, 0x3fb8aa3b, v19
	s_waitcnt lgkmcnt(0)
	v_mfma_f32_32x32x16_bf16 v[2:17], v[26:29], v[30:33], v[2:17]
	v_exp_f32_e32 v19, v19
	s_nop 10
	v_mul_f32_e32 v2, v18, v2
	v_bfe_u32 v18, v2, 16, 1
	v_add3_u32 v2, v2, v18, s33
	v_add_u32_e32 v18, v94, v68
	ds_write_b16_d16_hi v18, v2
	v_mul_f32_e32 v2, v19, v3
	v_cndmask_b32_e64 v3, v179, -v178, s[44:45]
	v_mul_f32_e32 v3, v3, v97
	v_mul_f32_e32 v3, 0x3fb8aa3b, v3
	v_exp_f32_e32 v3, v3
	v_bfe_u32 v19, v2, 16, 1
	v_add3_u32 v2, v2, v19, s33
	ds_write_b16_d16_hi v18, v2 offset:272
	v_mul_f32_e32 v2, v3, v4
	v_cndmask_b32_e64 v3, v179, -v178, s[46:47]
	v_mul_f32_e32 v3, v3, v98
	v_mul_f32_e32 v3, 0x3fb8aa3b, v3
	v_exp_f32_e32 v3, v3
	v_bfe_u32 v4, v2, 16, 1
	v_add3_u32 v2, v2, v4, s33
	ds_write_b16_d16_hi v18, v2 offset:544
	v_mul_f32_e32 v2, v3, v5
	v_cndmask_b32_e64 v4, v179, -v178, s[48:49]
	v_bfe_u32 v3, v2, 16, 1
	v_mul_f32_e32 v4, v4, v99
	v_mul_f32_e32 v4, 0x3fb8aa3b, v4
	v_add3_u32 v2, v2, v3, s33
	v_add_u32_e32 v3, v94, v72
	v_exp_f32_e32 v4, v4
	ds_write_b16_d16_hi v3, v2
	v_cndmask_b32_e64 v3, v179, -v178, s[50:51]
	v_mul_f32_e32 v3, v3, v100
	v_mul_f32_e32 v3, 0x3fb8aa3b, v3
	v_exp_f32_e32 v3, v3
	v_mul_f32_e32 v2, v4, v6
	v_bfe_u32 v4, v2, 16, 1
	v_add3_u32 v2, v2, v4, s33
	ds_write_b16_d16_hi v18, v2 offset:2176
	v_mul_f32_e32 v2, v3, v7
	v_cndmask_b32_e64 v3, v179, -v178, s[52:53]
	v_mul_f32_e32 v3, v3, v101
	v_mul_f32_e32 v3, 0x3fb8aa3b, v3
	v_exp_f32_e32 v3, v3
	v_bfe_u32 v4, v2, 16, 1
	v_add3_u32 v2, v2, v4, s33
	ds_write_b16_d16_hi v18, v2 offset:2448
	v_mul_f32_e32 v2, v3, v8
	v_cndmask_b32_e64 v3, v179, -v178, s[54:55]
	v_mul_f32_e32 v3, v3, v102
	v_mul_f32_e32 v3, 0x3fb8aa3b, v3
	v_bfe_u32 v4, v2, 16, 1
	v_exp_f32_e32 v3, v3
	v_add3_u32 v2, v2, v4, s33
	v_cndmask_b32_e64 v4, v179, -v178, s[56:57]
	v_mul_f32_e32 v4, v4, v103
	v_mul_f32_e32 v4, 0x3fb8aa3b, v4
	v_exp_f32_e32 v4, v4
	ds_write_b16_d16_hi v18, v2 offset:2720
	v_mul_f32_e32 v2, v3, v9
	v_bfe_u32 v3, v2, 16, 1
	v_add3_u32 v2, v2, v3, s33
	v_add_u32_e32 v3, v94, v77
	ds_write_b16_d16_hi v3, v2
; #define LAS __attribute__((address_space(3)))
; __device__ __forceinline__ unsigned f2bf(float f) { unsigned u = __builtin_bit_cast(unsigned, f); return (u + 0x7fffu + ((u >> 16) & 1u)) >> 16; }
; __device__ __forceinline__ int crow16(int r, int hi) { return (r & 3) + 8 * (r >> 2) + 4 * hi; }
; __device__ __forceinline__ void ret_out_unit(int unit, const bf16* RQ, const bf16* RK, const bf16* RV, const bf16* RG, const float* decay_l, const float* RETC, bf16* MIX, lds_t* lds, int tid, int lane, int wave) {
;     ...
;     for (int tt = 0; tt < 2; ++tt) { const int tile = wave * 2 + tt, it = tile >> 2, jt = tile & 3; f32x16 acc = {};
;         mma32<4>(acc, Qs + 32 * it * RT_LDD, RT_LDD, Ks + 32 * jt * RT_LDD, RT_LDD, lane);
;         const int j = 32 * jt + (lane & 31);
; #pragma unroll
;         for (int r = 0; r < 16; ++r) { const int i = 32 * it + crow16(r, lane >> 5); const float dd = (float)(i - j); const float w = acc[r] * __expf(dd >= 0.f ? lgf * dd : -lgb * dd);
;             *(LAS unsigned short*)(Ws + i * RT_LDK + j * 2) = (unsigned short)f2bf(w); } }
;     __syncthreads();
;     f32x16 o;
;     { const int it = wave >> 1, vt = wave & 1; f32x16 a1 = {}, a2 = {}, a3 = {};
;         mma32<8>(a1, Ws + 32 * it * RT_LDK, RT_LDK, Vt + 32 * vt * RT_LDK, RT_LDK, lane);
;         mma32<4>(a2, Qs + 32 * it * RT_LDD, RT_LDD, Sft + 32 * vt * RT_LDD, RT_LDD, lane);
;         mma32<4>(a3, Qs + 32 * it * RT_LDD, RT_LDD, Sbt + 32 * vt * RT_LDD, RT_LDD, lane);
	v_mul_f32_e32 v2, v4, v10
	v_cndmask_b32_e64 v4, v179, -v178, s[58:59]
	v_mul_f32_e32 v4, v4, v104
	v_mul_f32_e32 v4, 0x3fb8aa3b, v4
	v_exp_f32_e32 v4, v4
	v_bfe_u32 v3, v2, 16, 1
	v_add3_u32 v2, v2, v3, s33
	v_add_u32_e32 v3, v94, v79
	ds_write_b16_d16_hi v3, v2
	v_mul_f32_e32 v2, v4, v11
	v_cndmask_b32_e64 v4, v179, -v178, s[60:61]
	v_mul_f32_e32 v4, v4, v105
	v_mul_f32_e32 v4, 0x3fb8aa3b, v4
	v_exp_f32_e32 v4, v4
	v_bfe_u32 v3, v2, 16, 1
	v_add3_u32 v2, v2, v3, s33
	v_add_u32_e32 v3, v94, v81
	ds_write_b16_d16_hi v3, v2
	v_mul_f32_e32 v2, v4, v12
	v_cndmask_b32_e64 v4, v179, -v178, s[14:15]
	v_mul_f32_e32 v4, v4, v106
	v_mul_f32_e32 v4, 0x3fb8aa3b, v4
	v_exp_f32_e32 v4, v4
	v_bfe_u32 v3, v2, 16, 1
	v_add3_u32 v2, v2, v3, s33
	v_add_u32_e32 v3, v94, v83
	ds_write_b16_d16_hi v3, v2
	v_mul_f32_e32 v2, v4, v13
	v_cndmask_b32_e64 v4, v179, -v178, s[2:3]
	v_mul_f32_e32 v4, v4, v107
	v_mul_f32_e32 v4, 0x3fb8aa3b, v4
	v_exp_f32_e32 v4, v4
	v_bfe_u32 v3, v2, 16, 1
	v_add3_u32 v2, v2, v3, s33
	v_add_u32_e32 v3, v94, v85
	ds_write_b16_d16_hi v3, v2
	v_mul_f32_e32 v2, v4, v14
	v_cndmask_b32_e64 v4, v179, -v178, s[4:5]
	v_mul_f32_e32 v4, v4, v108
	v_mul_f32_e32 v4, 0x3fb8aa3b, v4
	v_exp_f32_e32 v4, v4
	v_bfe_u32 v3, v2, 16, 1
	v_add3_u32 v2, v2, v3, s33
	v_add_u32_e32 v3, v94, v87
	ds_write_b16_d16_hi v3, v2
	v_mul_f32_e32 v2, v4, v15
	v_cndmask_b32_e64 v4, v179, -v178, s[68:69]
	v_mul_f32_e32 v4, v4, v109
	v_mul_f32_e32 v4, 0x3fb8aa3b, v4
	v_exp_f32_e32 v4, v4
	v_bfe_u32 v3, v2, 16, 1
	v_add3_u32 v2, v2, v3, s33
	v_add_u32_e32 v3, v94, v89
	ds_write_b16_d16_hi v3, v2
	v_mul_f32_e32 v2, v4, v16
	v_cndmask_b32_e64 v4, v179, -v178, s[70:71]
	v_mul_f32_e32 v4, v4, v110
	v_mul_f32_e32 v4, 0x3fb8aa3b, v4
	v_exp_f32_e32 v4, v4
	v_bfe_u32 v3, v2, 16, 1
	v_add3_u32 v2, v2, v3, s33
	v_add_u32_e32 v3, v94, v91
	ds_write_b16_d16_hi v3, v2
	v_mul_f32_e32 v2, v4, v17
	v_bfe_u32 v3, v2, 16, 1
	v_add3_u32 v2, v2, v3, s33
	v_add_u32_e32 v3, v94, v93
	ds_write_b16_d16_hi v3, v2
	s_waitcnt lgkmcnt(0)
	s_barrier
	ds_read_b128 v[2:5], v164
	ds_read_b128 v[6:9], v165 offset:36864
	ds_read_b128 v[18:21], v164 offset:32
	ds_read_b128 v[22:25], v165 offset:36896
	s_waitcnt lgkmcnt(2)
	v_mfma_f32_32x32x16_bf16 v[2:17], v[2:5], v[6:9], 0
	s_waitcnt lgkmcnt(0)
	v_mfma_f32_32x32x16_bf16 v[2:17], v[18:21], v[22:25], v[2:17]
	ds_read_b128 v[18:21], v164 offset:64
	ds_read_b128 v[22:25], v165 offset:36928
	ds_read_b128 v[26:29], v164 offset:96
	ds_read_b128 v[30:33], v165 offset:36960
	s_waitcnt lgkmcnt(2)
	v_mfma_f32_32x32x16_bf16 v[2:17], v[18:21], v[22:25], v[2:17]
	s_waitcnt lgkmcnt(0)
	v_mfma_f32_32x32x16_bf16 v[2:17], v[26:29], v[30:33], v[2:17]
	ds_read_b128 v[18:21], v164 offset:128
	ds_read_b128 v[22:25], v165 offset:36992
	ds_read_b128 v[26:29], v164 offset:160
	ds_read_b128 v[30:33], v165 offset:37024
	s_waitcnt lgkmcnt(2)
	v_mfma_f32_32x32x16_bf16 v[2:17], v[18:21], v[22:25], v[2:17]
	s_waitcnt lgkmcnt(0)
	v_mfma_f32_32x32x16_bf16 v[2:17], v[26:29], v[30:33], v[2:17]
	ds_read_b128 v[18:21], v164 offset:192
	ds_read_b128 v[22:25], v165 offset:37056
	ds_read_b128 v[26:29], v164 offset:224
	ds_read_b128 v[30:33], v165 offset:37088
	s_waitcnt lgkmcnt(2)
	v_mfma_f32_32x32x16_bf16 v[2:17], v[18:21], v[22:25], v[2:17]
	ds_read_b128 v[34:37], v163
	ds_read_b128 v[18:21], v166 offset:54272
	ds_read_b128 v[180:183], v163 offset:32
	ds_read_b128 v[38:41], v166 offset:54304
	s_waitcnt lgkmcnt(4)
	v_mfma_f32_32x32x16_bf16 v[2:17], v[26:29], v[30:33], v[2:17]
	s_waitcnt lgkmcnt(2)
	v_mfma_f32_32x32x16_bf16 v[18:33], v[34:37], v[18:21], 0
	s_waitcnt lgkmcnt(0)
	v_mfma_f32_32x32x16_bf16 v[18:33], v[180:183], v[38:41], v[18:33]
	ds_read_b128 v[184:187], v163 offset:64
	ds_read_b128 v[38:41], v166 offset:54336
	ds_read_b128 v[188:191], v163 offset:96
	ds_read_b128 v[42:45], v166 offset:54368
	s_waitcnt lgkmcnt(2)
	v_mfma_f32_32x32x16_bf16 v[18:33], v[184:187], v[38:41], v[18:33]
	ds_read_b128 v[38:41], v166 offset:63488
	ds_read_b128 v[192:195], v166 offset:63520
	s_waitcnt lgkmcnt(2)
	v_mfma_f32_32x32x16_bf16 v[18:33], v[188:191], v[42:45], v[18:33]
	s_waitcnt lgkmcnt(1)
	v_mfma_f32_32x32x16_bf16 v[34:49], v[34:37], v[38:41], 0
	s_waitcnt lgkmcnt(0)
	v_mfma_f32_32x32x16_bf16 v[34:49], v[180:183], v[192:195], v[34:49]
	ds_read_b128 v[180:183], v166 offset:63552
	ds_read_b128 v[192:195], v166 offset:63584
	s_waitcnt lgkmcnt(0)
	s_barrier
; #define LAS __attribute__((address_space(3)))
; __device__ __forceinline__ int crow16(int r, int hi) { return (r & 3) + 8 * (r >> 2) + 4 * hi; }
; __device__ __forceinline__ void ret_out_unit(int unit, const bf16* RQ, const bf16* RK, const bf16* RV, const bf16* RG, const float* decay_l, const float* RETC, bf16* MIX, lds_t* lds, int tid, int lane, int wave) {
;     ...
;     f32x16 o;
;     { const int it = wave >> 1, vt = wave & 1; f32x16 a1 = {}, a2 = {}, a3 = {};
;         mma32<8>(a1, Ws + 32 * it * RT_LDK, RT_LDK, Vt + 32 * vt * RT_LDK, RT_LDK, lane);
;         mma32<4>(a2, Qs + 32 * it * RT_LDD, RT_LDD, Sft + 32 * vt * RT_LDD, RT_LDD, lane);
;         mma32<4>(a3, Qs + 32 * it * RT_LDD, RT_LDD, Sbt + 32 * vt * RT_LDD, RT_LDD, lane);
; #pragma unroll
;         for (int r = 0; r < 16; ++r) { const int i = 32 * it + crow16(r, lane >> 5); o[r] = a1[r] + __expf(lgf * (float)(i + 1)) * a2[r] + __expf(lgb * (float)(128 - i)) * a3[r]; } }
;     __syncthreads();
;     { const int it = wave >> 1, vt = wave & 1; LAS float* Os = (LAS float*)Ws;
; #pragma unroll
;         for (int r = 0; r < 16; ++r) Os[(32 * it + crow16(r, lane >> 5)) * 65 + 32 * vt + (lane & 31)] = o[r]; }
;     __syncthreads();
	v_mfma_f32_32x32x16_bf16 v[34:49], v[184:187], v[180:183], v[34:49]
	v_mul_f32_e32 v180, v179, v111
	v_mul_f32_e32 v180, 0x3fb8aa3b, v180
	v_mul_f32_e32 v181, v178, v112
	v_mul_f32_e32 v182, v179, v113
	v_exp_f32_e32 v180, v180
	v_mul_f32_e32 v181, 0x3fb8aa3b, v181
	v_mul_f32_e32 v182, 0x3fb8aa3b, v182
	v_mfma_f32_32x32x16_bf16 v[34:49], v[188:191], v[192:195], v[34:49]
	v_exp_f32_e32 v181, v181
	v_exp_f32_e32 v182, v182
	v_fma_f32 v2, v180, v18, v2
	v_mul_f32_e32 v18, v179, v131
	v_mul_f32_e32 v18, 0x3fb8aa3b, v18
	v_fma_f32 v3, v182, v19, v3
	v_mul_f32_e32 v19, v178, v132
	s_nop 4
	v_fmac_f32_e32 v2, v181, v34
	v_mul_f32_e32 v34, v179, v133
	v_exp_f32_e32 v18, v18
	v_mul_f32_e32 v19, 0x3fb8aa3b, v19
	v_mul_f32_e32 v34, 0x3fb8aa3b, v34
	v_exp_f32_e32 v19, v19
	v_exp_f32_e32 v34, v34
	v_fma_f32 v4, v18, v20, v4
	v_mul_f32_e32 v18, v179, v135
	v_mul_f32_e32 v20, v179, v137
	v_fmac_f32_e32 v4, v19, v36
	v_fma_f32 v5, v34, v21, v5
	v_mul_f32_e32 v18, 0x3fb8aa3b, v18
	v_mul_f32_e32 v19, v178, v136
	v_mul_f32_e32 v20, 0x3fb8aa3b, v20
	v_mul_f32_e32 v21, v178, v138
	v_exp_f32_e32 v18, v18
	v_mul_f32_e32 v19, 0x3fb8aa3b, v19
	v_exp_f32_e32 v20, v20
	v_mul_f32_e32 v21, 0x3fb8aa3b, v21
	v_exp_f32_e32 v19, v19
	v_exp_f32_e32 v21, v21
	v_fma_f32 v6, v18, v22, v6
	v_fma_f32 v7, v20, v23, v7
	v_mul_f32_e32 v18, v179, v139
	v_mul_f32_e32 v20, v179, v141
	v_fmac_f32_e32 v6, v19, v38
	v_fmac_f32_e32 v7, v21, v39
	v_mul_f32_e32 v18, 0x3fb8aa3b, v18
	v_mul_f32_e32 v19, v178, v140
	v_mul_f32_e32 v20, 0x3fb8aa3b, v20
	v_mul_f32_e32 v21, v178, v142
	v_exp_f32_e32 v18, v18
	v_mul_f32_e32 v19, 0x3fb8aa3b, v19
	v_exp_f32_e32 v20, v20
	v_mul_f32_e32 v21, 0x3fb8aa3b, v21
	v_exp_f32_e32 v19, v19
	v_exp_f32_e32 v21, v21
	v_fma_f32 v8, v18, v24, v8
	v_fma_f32 v9, v20, v25, v9
	v_mul_f32_e32 v18, v179, v143
	v_mul_f32_e32 v20, v179, v145
	v_fmac_f32_e32 v8, v19, v40
	v_fmac_f32_e32 v9, v21, v41
	v_mul_f32_e32 v18, 0x3fb8aa3b, v18
	v_mul_f32_e32 v19, v178, v144
	v_mul_f32_e32 v20, 0x3fb8aa3b, v20
	v_mul_f32_e32 v21, v178, v146
	v_exp_f32_e32 v18, v18
	v_mul_f32_e32 v19, 0x3fb8aa3b, v19
	v_exp_f32_e32 v20, v20
	v_mul_f32_e32 v21, 0x3fb8aa3b, v21
	v_exp_f32_e32 v19, v19
	v_exp_f32_e32 v21, v21
	v_fma_f32 v10, v18, v26, v10
	v_fma_f32 v11, v20, v27, v11
	v_mul_f32_e32 v18, v179, v147
	v_mul_f32_e32 v20, v179, v149
	v_fmac_f32_e32 v10, v19, v42
	v_fmac_f32_e32 v11, v21, v43
	v_mul_f32_e32 v18, 0x3fb8aa3b, v18
	v_mul_f32_e32 v19, v178, v148
	v_mul_f32_e32 v20, 0x3fb8aa3b, v20
	v_mul_f32_e32 v21, v178, v150
	v_exp_f32_e32 v18, v18
	v_mul_f32_e32 v19, 0x3fb8aa3b, v19
	v_exp_f32_e32 v20, v20
	v_mul_f32_e32 v21, 0x3fb8aa3b, v21
	v_exp_f32_e32 v19, v19
	v_exp_f32_e32 v21, v21
	v_fma_f32 v12, v18, v28, v12
	v_fma_f32 v13, v20, v29, v13
	v_mul_f32_e32 v18, v179, v151
	v_mul_f32_e32 v20, v179, v153
	v_mul_f32_e32 v183, v178, v130
	v_fmac_f32_e32 v12, v19, v44
	v_fmac_f32_e32 v13, v21, v45
	v_mul_f32_e32 v18, 0x3fb8aa3b, v18
	v_mul_f32_e32 v19, v178, v152
	v_mul_f32_e32 v20, 0x3fb8aa3b, v20
	v_mul_f32_e32 v21, v178, v154
	v_mul_f32_e32 v183, 0x3fb8aa3b, v183
	v_exp_f32_e32 v18, v18
	v_mul_f32_e32 v19, 0x3fb8aa3b, v19
	v_exp_f32_e32 v20, v20
	v_mul_f32_e32 v21, 0x3fb8aa3b, v21
	v_exp_f32_e32 v183, v183
	v_exp_f32_e32 v19, v19
	v_exp_f32_e32 v21, v21
	v_fma_f32 v14, v18, v30, v14
	v_fma_f32 v15, v20, v31, v15
	v_mul_f32_e32 v18, v179, v155
	v_mul_f32_e32 v20, v179, v157
	v_fmac_f32_e32 v3, v183, v35
	v_mul_f32_e32 v35, v178, v134
	v_fmac_f32_e32 v14, v19, v46
	v_fmac_f32_e32 v15, v21, v47
	v_mul_f32_e32 v18, 0x3fb8aa3b, v18
	v_mul_f32_e32 v19, v178, v156
	v_mul_f32_e32 v20, 0x3fb8aa3b, v20
	v_mul_f32_e32 v21, v178, v158
	v_mul_f32_e32 v35, 0x3fb8aa3b, v35
	v_exp_f32_e32 v18, v18
	v_mul_f32_e32 v19, 0x3fb8aa3b, v19
	v_exp_f32_e32 v20, v20
	v_mul_f32_e32 v21, 0x3fb8aa3b, v21
	v_exp_f32_e32 v35, v35
	v_exp_f32_e32 v19, v19
	v_exp_f32_e32 v21, v21
	v_fma_f32 v16, v18, v32, v16
	v_fmac_f32_e32 v17, v20, v33
	v_fmac_f32_e32 v5, v35, v37
	v_fmac_f32_e32 v16, v19, v48
	v_fmac_f32_e32 v17, v21, v49
	ds_write2_b32 v167, v2, v3 offset1:65
	ds_write_b32 v167, v4 offset:520
	ds_write_b32 v168, v5
	v_add_u32_e32 v2, 0x800, v167
	ds_write2_b32 v2, v6, v7 offset0:8 offset1:73
	ds_write_b32 v167, v8 offset:2600
	ds_write_b32 v169, v9
	ds_write_b32 v170, v10
	ds_write_b32 v171, v11
	ds_write_b32 v172, v12
	ds_write_b32 v173, v13
	ds_write_b32 v174, v14
	ds_write_b32 v175, v15
	ds_write_b32 v176, v16
	ds_write_b32 v177, v17
	s_waitcnt lgkmcnt(0)
	s_barrier
; #define LAS __attribute__((address_space(3)))
; __device__ __forceinline__ unsigned pk2(float lo, float hi) { return f2bf(lo) | (f2bf(hi) << 16); }
; __device__ __forceinline__ void ret_out_unit(int unit, const bf16* RQ, const bf16* RK, const bf16* RV, const bf16* RG, const float* decay_l, const float* RETC, bf16* MIX, lds_t* lds, int tid, int lane, int wave) {
;     ...
;     { const int i = tid >> 2, c0 = (tid & 3) * 16; const LAS float* Os = (const LAS float*)Ws + i * 65 + c0; float vals[16]; float ss = 0.f;
; #pragma unroll
;         for (int e = 0; e < 16; ++e) { vals[e] = Os[e]; ss += vals[e] * vals[e]; }
;         ss += __shfl_xor(ss, 1); ss += __shfl_xor(ss, 2);
;         const float rs = rsqrtf(ss * (1.0f / 64.0f) + EPSN);
;         bf16* dst = MIX + (size_t)(m0 + i) * DM + h * 64 + c0;
; #pragma unroll
;         for (int q = 0; q < 2; ++q) { const v4u gw = gpre[q]; v4u ow;
; #pragma unroll
;             for (int e = 0; e < 4; ++e) ow[e] = pk2(vals[q * 8 + 2 * e] * rs * bflo(gw[e]), vals[q * 8 + 2 * e + 1] * rs * bfhi(gw[e]));
;             *(v4u*)(dst + 8 * q) = ow; } }
;     __syncthreads();
	ds_read2_b32 v[2:3], v159 offset0:12 offset1:13
	ds_read2_b32 v[4:5], v159 offset0:14 offset1:15
	ds_read2_b32 v[16:17], v159 offset0:10 offset1:11
	ds_read2_b32 v[10:11], v159 offset0:2 offset1:3
	ds_read2_b32 v[8:9], v159 offset0:6 offset1:7
	ds_read2_b32 v[22:23], v159 offset0:4 offset1:5
	ds_read2_b32 v[14:15], v159 offset1:1
	ds_read2_b32 v[28:29], v159 offset0:8 offset1:9
	s_waitcnt lgkmcnt(4)
	v_pk_mul_f32 v[24:25], v[10:11], v[10:11]
	s_waitcnt lgkmcnt(3)
	v_pk_mul_f32 v[32:33], v[8:9], v[8:9]
	s_waitcnt lgkmcnt(2)
	v_pk_mul_f32 v[34:35], v[22:23], v[22:23]
	s_waitcnt lgkmcnt(1)
	v_pk_mul_f32 v[26:27], v[14:15], v[14:15]
	s_waitcnt lgkmcnt(0)
	v_pk_mul_f32 v[36:37], v[28:29], v[28:29]
	v_add_f32_e32 v26, v26, v27
	v_add_f32_e32 v24, v26, v24
	v_add_f32_e32 v24, v24, v25
	v_add_f32_e32 v24, v24, v34
	v_add_f32_e32 v24, v24, v35
	v_add_f32_e32 v24, v24, v32
	v_add_f32_e32 v24, v24, v33
	v_add_f32_e32 v24, v24, v36
	v_pk_mul_f32 v[38:39], v[16:17], v[16:17]
	v_add_f32_e32 v24, v24, v37
	v_add_f32_e32 v24, v24, v38
	v_pk_mul_f32 v[20:21], v[2:3], v[2:3]
	v_and_b32_e32 v7, 64, v218
	v_add_f32_e32 v24, v24, v39
	v_xor_b32_e32 v6, 1, v218
	v_add_u32_e32 v7, 64, v7
	v_add_f32_e32 v20, v24, v20
	v_pk_mul_f32 v[18:19], v[4:5], v[4:5]
	v_cmp_lt_i32_e32 vcc, v6, v7
	v_add_f32_e32 v20, v20, v21
	v_add_f32_e32 v18, v20, v18
	v_cndmask_b32_e32 v6, v218, v6, vcc
	v_lshlrev_b32_e32 v40, 2, v6
	v_add_f32_e32 v20, v18, v19
	ds_bpermute_b32 v24, v40, v20
	v_xor_b32_e32 v6, 2, v218
	v_cmp_lt_i32_e32 vcc, v6, v7
	v_mov_b32_e32 v12, v14
	v_mov_b32_e32 v13, v10
	v_cndmask_b32_e32 v6, v218, v6, vcc
	v_lshlrev_b32_e32 v41, 2, v6
	s_waitcnt lgkmcnt(0)
	v_add_f32_e32 v25, v20, v24
	ds_bpermute_b32 v26, v41, v25
	v_lshlrev_b64 v[6:7], 11, v[60:61]
	v_lshl_add_u64 v[6:7], s[0:1], 0, v[6:7]
	s_mov_b32 s0, 0x800000
	v_mov_b32_e32 v10, v15
	s_waitcnt lgkmcnt(0)
	v_add_f32_e32 v25, v25, v26
	v_fmamk_f32 v25, v25, 0x3c800000, v213
	v_mul_f32_e32 v26, 0x4b800000, v25
	v_cmp_gt_f32_e32 vcc, s0, v25
	v_mov_b32_e32 v19, v8
	v_mov_b32_e32 v8, v23
	v_cndmask_b32_e32 v25, v25, v26, vcc
	v_rsq_f32_e32 v26, v25
	s_waitcnt vmcnt(0)
	v_lshlrev_b32_e32 v15, 16, v55
	v_lshlrev_b32_e32 v14, 16, v54
	v_and_b32_e32 v31, 0xffff0000, v55
	v_mul_f32_e32 v27, 0x45800000, v26
	v_cndmask_b32_e32 v26, v26, v27, vcc
	v_and_b32_e32 v30, 0xffff0000, v54
	v_mov_b32_e32 v18, v22
	v_and_b32_e32 v23, 0xffff0000, v57
	v_and_b32_e32 v22, 0xffff0000, v56
	v_pk_mul_f32 v[12:13], v[12:13], v[26:27] op_sel_hi:[1,0]
	v_pk_mul_f32 v[10:11], v[10:11], v[26:27] op_sel_hi:[1,0]
	v_pk_mul_f32 v[8:9], v[8:9], v[26:27] op_sel_hi:[1,0]
	v_lshlrev_b32_e32 v21, 16, v57
	v_lshlrev_b32_e32 v20, 16, v56
	v_pk_mul_f32 v[12:13], v[12:13], v[14:15]
	v_pk_mul_f32 v[10:11], v[10:11], v[30:31]
	v_pk_mul_f32 v[14:15], v[18:19], v[26:27] op_sel_hi:[1,0]
	v_pk_mul_f32 v[8:9], v[8:9], v[22:23]
	v_pk_mul_f32 v[14:15], v[14:15], v[20:21]
	v_bfe_u32 v18, v9, 16, 1
	v_bfe_u32 v19, v8, 16, 1
	v_bfe_u32 v20, v11, 16, 1
	v_bfe_u32 v21, v10, 16, 1
	v_add3_u32 v21, v10, v21, s33
	v_add3_u32 v20, v11, v20, s33
	v_add3_u32 v8, v8, v19, s33
	v_add3_u32 v9, v9, v18, s33
	v_bfe_u32 v10, v12, 16, 1
	v_bfe_u32 v11, v13, 16, 1
	v_bfe_u32 v18, v14, 16, 1
	v_bfe_u32 v19, v15, 16, 1
	v_add3_u32 v15, v15, v19, s33
	v_add3_u32 v14, v14, v18, s33
	v_add3_u32 v11, v13, v11, s33
	v_add3_u32 v10, v12, v10, s33
	v_lshl_add_u64 v[6:7], v[6:7], 0, s[84:85]
	v_lshrrev_b32_e32 v12, 16, v10
	v_lshrrev_b32_e32 v13, 16, v11
	v_lshrrev_b32_e32 v10, 16, v14
	v_lshrrev_b32_e32 v11, 16, v15
	v_lshl_add_u64 v[6:7], v[6:7], 0, v[0:1]
	v_mov_b32_e32 v24, v28
	v_mov_b32_e32 v25, v16
	v_and_or_b32 v11, v9, s87, v11
	v_and_or_b32 v10, v8, s87, v10
	v_and_or_b32 v9, v20, s87, v13
	v_and_or_b32 v8, v21, s87, v12
	v_mov_b32_e32 v16, v29
	global_store_dwordx4 v[6:7], v[8:11], off
	v_and_b32_e32 v13, 0xffff0000, v51
	v_and_b32_e32 v12, 0xffff0000, v50
	v_pk_mul_f32 v[8:9], v[24:25], v[26:27] op_sel_hi:[1,0]
	v_lshlrev_b32_e32 v11, 16, v51
	v_lshlrev_b32_e32 v10, 16, v50
	v_pk_mul_f32 v[8:9], v[8:9], v[10:11]
	v_pk_mul_f32 v[10:11], v[16:17], v[26:27] op_sel_hi:[1,0]
	v_lshlrev_b32_e32 v15, 16, v53
	v_pk_mul_f32 v[10:11], v[10:11], v[12:13]
	v_mov_b32_e32 v13, v4
	v_mov_b32_e32 v4, v3
	v_mov_b32_e32 v12, v2
	v_pk_mul_f32 v[2:3], v[4:5], v[26:27] op_sel_hi:[1,0]
	v_and_b32_e32 v5, 0xffff0000, v53
	v_and_b32_e32 v4, 0xffff0000, v52
	v_pk_mul_f32 v[12:13], v[12:13], v[26:27] op_sel_hi:[1,0]
	v_lshlrev_b32_e32 v14, 16, v52
	v_pk_mul_f32 v[2:3], v[2:3], v[4:5]
	v_pk_mul_f32 v[12:13], v[12:13], v[14:15]
	v_bfe_u32 v4, v3, 16, 1
	v_bfe_u32 v5, v2, 16, 1
	v_bfe_u32 v14, v11, 16, 1
	v_bfe_u32 v15, v10, 16, 1
	v_add3_u32 v10, v10, v15, s33
	v_add3_u32 v11, v11, v14, s33
	v_add3_u32 v2, v2, v5, s33
	v_add3_u32 v3, v3, v4, s33
	v_bfe_u32 v4, v8, 16, 1
	v_bfe_u32 v5, v9, 16, 1
	v_bfe_u32 v14, v12, 16, 1
	v_bfe_u32 v15, v13, 16, 1
	v_add3_u32 v13, v13, v15, s33
	v_add3_u32 v12, v12, v14, s33
	v_add3_u32 v5, v9, v5, s33
	v_add3_u32 v4, v8, v4, s33
	v_lshrrev_b32_e32 v8, 16, v4
	v_lshrrev_b32_e32 v9, 16, v5
	v_lshrrev_b32_e32 v4, 16, v12
	v_lshrrev_b32_e32 v5, 16, v13
	v_and_or_b32 v5, v3, s87, v5
	v_and_or_b32 v4, v2, s87, v4
	v_and_or_b32 v3, v11, s87, v9
	v_and_or_b32 v2, v10, s87, v8
	global_store_dwordx4 v[6:7], v[2:5], off offset:16
	s_barrier
